# P5 conv: the sample-row tasks move from threads 0..40959 (which already carry three prompt tasks) to threads 65536..106495 (two prompt tasks)
# speedup vs baseline: 1.0132x; 1.0064x over previous
.LBB0_1003:
	s_or_b64 exec, exec, s[10:11]
	s_add_u32 s36, s42, 0x10f94000
	s_mov_b32 s0, 0xa000
	s_addc_u32 s37, s43, 0
	v_add_u32_e32 v128, 0xffff0000, v128
	v_lshlrev_b32_e32 v129, 3, v128
	v_cmp_gt_u32_e32 vcc, s0, v128
	s_and_saveexec_b64 s[0:1], vcc
	s_cbranch_execz .LBB0_1022
	s_add_u32 s6, s40, 0xaa5c000
	s_addc_u32 s7, s41, 0
	s_add_u32 s10, s40, 0xaa5e800
	s_addc_u32 s11, s41, 0
	s_add_u32 s12, s40, 0xaa61000
	s_addc_u32 s13, s41, 0
	s_lshl_b32 s18, s34, 3
	s_mov_b64 s[14:15], 0
	s_movk_i32 s19, 0x2600
	v_mov_b64_e32 v[80:81], s[76:77]
	s_movk_i32 s20, 0x1000
	s_movk_i32 s21, 0x2800
	v_mov_b64_e32 v[82:83], s[46:47]
	v_mov_b32_e32 v85, 0
	s_movk_i32 s22, 0xc00
	s_branch .LBB0_1006
